# plus SSD row-sum reduction via v_permlane16/32_swap (no LDS round trips on the critical waves)
# baseline (speedup 1.0000x reference)
.LBB0_360:
	v_add_u32_e32 v156, v106, v107
	ds_read_b128 v[160:163], v156 offset:34816
	ds_read_b128 v[164:167], v156 offset:34880
	ds_read_b128 v[168:171], v156 offset:17408
	ds_read_b128 v[172:175], v156 offset:17472
	ds_read_b128 v[176:179], v138
	ds_read_b128 v[180:183], v138 offset:64
	ds_read_b128 v[184:187], v138 offset:4352
	ds_read_b128 v[188:191], v138 offset:4416
	ds_read_b128 v[192:195], v156 offset:34944
	ds_read_b128 v[202:205], v156 offset:35008
	ds_read_b128 v[206:209], v156 offset:17536
	ds_read_b128 v[210:213], v156 offset:17600
	ds_read_b128 v[214:217], v138 offset:128
	ds_read_b128 v[236:239], v138 offset:192
	ds_read_b128 v[240:243], v138 offset:4480
	ds_read_b128 v[244:247], v138 offset:4544
	s_waitcnt lgkmcnt(11)
	v_mfma_f32_16x16x32_bf16 v[248:251], v[160:163], v[176:179], 0
	v_mfma_f32_16x16x32_bf16 v[176:179], v[168:171], v[176:179], 0
	s_waitcnt lgkmcnt(9)
	v_mfma_f32_16x16x32_bf16 v[160:163], v[160:163], v[184:187], 0
	v_mfma_f32_16x16x32_bf16 v[168:171], v[168:171], v[184:187], 0
	v_mfma_f32_16x16x32_bf16 v[184:187], v[164:167], v[180:183], v[248:251]
	v_mfma_f32_16x16x32_bf16 v[176:179], v[172:175], v[180:183], v[176:179]
	s_waitcnt lgkmcnt(8)
	v_mfma_f32_16x16x32_bf16 v[160:163], v[164:167], v[188:191], v[160:163]
	v_mfma_f32_16x16x32_bf16 v[164:167], v[172:175], v[188:191], v[168:171]
	s_waitcnt lgkmcnt(3)
	v_mfma_f32_16x16x32_bf16 v[168:171], v[192:195], v[214:217], v[184:187]
	v_mfma_f32_16x16x32_bf16 v[172:175], v[206:209], v[214:217], v[176:179]
	s_waitcnt lgkmcnt(1)
	v_mfma_f32_16x16x32_bf16 v[160:163], v[192:195], v[240:243], v[160:163]
	s_nop 0
	ds_read_b128 v[176:179], v139
	ds_read_b128 v[180:183], v140 offset:52224
	ds_read_b128 v[184:187], v141 offset:54528
	ds_read_b128 v[188:191], v142 offset:56832
	ds_read_b128 v[192:195], v143 offset:59136
	v_mfma_f32_16x16x32_bf16 v[164:167], v[206:209], v[240:243], v[164:167]
	s_waitcnt lgkmcnt(5)
	v_mfma_f32_16x16x32_bf16 v[160:163], v[202:205], v[244:247], v[160:163]
	v_mfma_f32_16x16x32_bf16 v[168:171], v[202:205], v[236:239], v[168:171]
	v_mfma_f32_16x16x32_bf16 v[172:175], v[210:213], v[236:239], v[172:175]
	v_mfma_f32_16x16x32_bf16 v[164:167], v[210:213], v[244:247], v[164:167]
	ds_read_b32 v55, v109
	ds_read_b128 v[202:205], v127
	s_waitcnt lgkmcnt(0)
	v_pk_add_f32 v[198:199], v[54:55], v[202:203] op_sel:[1,0] op_sel_hi:[1,1] neg_lo:[0,1] neg_hi:[0,1]
	v_pk_add_f32 v[222:223], v[54:55], v[204:205] op_sel:[1,0] op_sel_hi:[1,1] neg_lo:[0,1] neg_hi:[0,1]
	v_pk_mul_f32 v[198:199], v[198:199], s[100:101]
	v_pk_mul_f32 v[222:223], v[222:223], s[100:101]
	v_exp_f32_e32 v198, v198
	v_exp_f32_e32 v199, v199
	v_exp_f32_e32 v222, v222
	v_exp_f32_e32 v223, v223
	v_pk_mul_f32 v[198:199], v[172:173], v[198:199]
	v_pk_mul_f32 v[222:223], v[174:175], v[222:223]
	v_cndmask_b32_e64 v198, v198, 0, s[42:43]
	v_cndmask_b32_e64 v199, 0, v199, s[44:45]
	v_cndmask_b32_e64 v222, v222, 0, s[46:47]
	v_cndmask_b32_e64 v223, v223, 0, s[48:49]
	v_cvt_pk_bf16_f32 v172, v198, v199
	v_cvt_pk_bf16_f32 v173, v222, v223
	ds_write_b64 v144, v[172:173]
	ds_read_b32 v89, v110
	ds_read_b128 v[172:175], v127
	v_mul_f32_e32 v55, 0x3fb8aa3b, v55
	v_exp_f32_e32 v154, v55
	s_waitcnt lgkmcnt(0)
	v_mul_f32_e32 v55, 0x3fb8aa3b, v89
	v_pk_add_f32 v[198:199], v[88:89], v[172:173] op_sel:[1,0] op_sel_hi:[1,1] neg_lo:[0,1] neg_hi:[0,1]
	v_pk_add_f32 v[222:223], v[88:89], v[174:175] op_sel:[1,0] op_sel_hi:[1,1] neg_lo:[0,1] neg_hi:[0,1]
	v_pk_mul_f32 v[198:199], v[198:199], s[100:101]
	v_pk_mul_f32 v[222:223], v[222:223], s[100:101]
	v_exp_f32_e32 v198, v198
	v_exp_f32_e32 v199, v199
	v_exp_f32_e32 v222, v222
	v_exp_f32_e32 v223, v223
	v_exp_f32_e32 v206, v55
	v_pk_mul_f32 v[198:199], v[164:165], v[198:199]
	v_pk_mul_f32 v[222:223], v[166:167], v[222:223]
	v_cndmask_b32_e64 v198, v198, 0, s[50:51]
	v_cndmask_b32_e64 v199, 0, v199, s[52:53]
	v_cndmask_b32_e64 v222, v222, 0, s[54:55]
	v_cndmask_b32_e64 v223, v223, 0, s[56:57]
	v_cvt_pk_bf16_f32 v164, v198, v199
	v_cvt_pk_bf16_f32 v165, v222, v223
	ds_write_b64 v145, v[164:165]
	v_mul_f32_e32 v54, 0x3fb8aa3b, v54
	v_exp_f32_e32 v54, v54
	ds_read_b128 v[164:167], v146 offset:52224
	v_add_u32_e32 v159, v108, v111
	ds_read_b128 v[172:175], v159
	v_pk_mul_f32 v[50:51], v[50:51], v[54:55] op_sel_hi:[1,0]
	v_pk_mul_f32 v[48:49], v[48:49], v[54:55] op_sel_hi:[1,0]
	v_pk_mul_f32 v[42:43], v[42:43], v[54:55] op_sel_hi:[1,0]
	v_pk_mul_f32 v[40:41], v[40:41], v[54:55] op_sel_hi:[1,0]
	v_pk_mul_f32 v[46:47], v[46:47], v[54:55] op_sel_hi:[1,0]
	v_pk_mul_f32 v[44:45], v[44:45], v[54:55] op_sel_hi:[1,0]
	v_pk_mul_f32 v[38:39], v[38:39], v[54:55] op_sel_hi:[1,0]
	v_pk_mul_f32 v[36:37], v[36:37], v[54:55] op_sel_hi:[1,0]
	v_mfma_f32_16x16x32_bf16 v[48:51], v[180:183], v[176:179], v[48:51]
	v_add_u32_e32 v54, v112, v113
	v_mfma_f32_16x16x32_bf16 v[40:43], v[184:187], v[176:179], v[40:43]
	v_mfma_f32_16x16x32_bf16 v[44:47], v[188:191], v[176:179], v[44:47]
	v_mfma_f32_16x16x32_bf16 v[36:39], v[192:195], v[176:179], v[36:39]
	ds_read_b128 v[176:179], v147 offset:54528
	s_waitcnt lgkmcnt(1)
	v_mfma_f32_16x16x32_bf16 v[48:51], v[164:167], v[172:175], v[48:51]
	ds_read_b128 v[164:167], v148 offset:56832
	ds_read_b128 v[180:183], v149 offset:59136
	s_waitcnt lgkmcnt(0)
	s_barrier
	s_waitcnt lgkmcnt(2)
	v_mfma_f32_16x16x32_bf16 v[40:43], v[176:179], v[172:175], v[40:43]
	ds_read_b128 v[176:179], v54
	ds_read_b128 v[184:187], v150
	v_add_u32_e32 v54, v112, v111
	s_waitcnt lgkmcnt(3)
	v_mfma_f32_16x16x32_bf16 v[44:47], v[164:167], v[172:175], v[44:47]
	ds_read_b128 v[164:167], v150 offset:2304
	ds_read_b128 v[188:191], v150 offset:64
	ds_read_b128 v[192:195], v54
	ds_read_b128 v[202:205], v150 offset:2368
	s_waitcnt lgkmcnt(6)
	v_mfma_f32_16x16x32_bf16 v[36:39], v[180:183], v[172:175], v[36:39]
	v_mul_f32_e64 v170, v170, v154
	v_mul_f32_e64 v171, v171, v154
	v_pk_mul_f32 v[168:169], v[168:169], v[154:155] op_sel_hi:[1,0]
	v_pk_mul_f32 v[162:163], v[162:163], v[206:207] op_sel_hi:[1,0]
	v_pk_mul_f32 v[160:161], v[160:161], v[206:207] op_sel_hi:[1,0]
	s_waitcnt lgkmcnt(4)
	v_mfma_f32_16x16x32_bf16 v[168:171], v[176:179], v[184:187], v[168:171]
	v_cvt_pk_bf16_f32 v54, v48, v49
	v_cvt_pk_bf16_f32 v55, v50, v51
	v_cvt_pk_bf16_f32 v172, v40, v41
	v_cvt_pk_bf16_f32 v173, v42, v43
	v_add_u32_e32 v157, 0x8800, v151
	s_waitcnt lgkmcnt(3)
	v_mfma_f32_16x16x32_bf16 v[160:163], v[176:179], v[164:167], v[160:163]
	ds_write2_b64 v157, v[54:55], v[172:173] offset1:4
	v_cvt_pk_bf16_f32 v54, v44, v45
	v_cvt_pk_bf16_f32 v55, v46, v47
	s_waitcnt lgkmcnt(2)
	v_mfma_f32_16x16x32_bf16 v[164:167], v[192:195], v[188:191], v[168:171]
	v_cmp_lt_i32_e32 vcc, v225, v220
	v_lshl_add_u64 v[92:93], v[86:87], 0, v[92:93]
	s_nop 0
	v_cvt_pk_bf16_f32 v168, v36, v37
	v_cvt_pk_bf16_f32 v169, v38, v39
	ds_write2_b64 v157, v[54:55], v[168:169] offset0:8 offset1:12
	v_cndmask_b32_e32 v54, v218, v225, vcc
	v_lshlrev_b32_e32 v153, 2, v54
	s_waitcnt vmcnt(9)
	v_lshlrev_b32_e32 v54, 16, v52
	v_and_b32_e32 v55, 0xffff0000, v52
	v_mul_f32_e32 v52, 0xbfb8aa3b, v54
	v_exp_f32_e32 v52, v52
	v_mul_f32_e32 v89, 0xbfb8aa3b, v55
	v_exp_f32_e32 v89, v89
	ds_read_b64 v[168:169], v128
	v_add_f32_e32 v52, 1.0, v52
	v_rcp_f32_e32 v170, v52
	v_add_f32_e32 v52, 1.0, v89
	v_rcp_f32_e32 v171, v52
	s_waitcnt lgkmcnt(0)
	v_lshlrev_b32_e32 v172, 16, v168
	v_and_b32_e32 v173, 0xffff0000, v168
	v_pk_fma_f32 v[164:165], v[0:1], v[172:173], v[164:165]
	v_pk_mul_f32 v[54:55], v[170:171], v[54:55]
	v_lshlrev_b32_e32 v52, 16, v53
	v_pk_mul_f32 v[164:165], v[54:55], v[164:165]
	v_and_b32_e32 v53, 0xffff0000, v53
	v_mul_f32_e32 v54, 0xbfb8aa3b, v52
	v_exp_f32_e32 v89, v54
	v_mul_f32_e32 v54, 0xbfb8aa3b, v53
	v_exp_f32_e32 v154, v54
	v_lshlrev_b32_e32 v168, 16, v169
	v_add_f32_e32 v89, 1.0, v89
	v_rcp_f32_e32 v170, v89
	v_add_f32_e32 v89, 1.0, v154
	v_rcp_f32_e32 v171, v89
	v_and_b32_e32 v169, 0xffff0000, v169
	v_pk_fma_f32 v[166:167], v[0:1], v[168:169], v[166:167]
	v_pk_mul_f32 v[54:55], v[164:165], v[164:165]
	v_pk_mul_f32 v[52:53], v[170:171], v[52:53]
	v_add_f32_e32 v54, v54, v55
	v_pk_mul_f32 v[166:167], v[52:53], v[166:167]
	v_cmp_lt_i32_e32 vcc, v226, v220
	v_pk_mul_f32 v[52:53], v[166:167], v[166:167]
	s_nop 0
	v_add_f32_e32 v52, v52, v54
	v_add_f32_e32 v89, v53, v52
	v_mov_b32_e32 v168, v89
	v_cndmask_b32_e32 v154, v218, v226, vcc
	v_lshlrev_b32_e32 v154, 2, v154
	v_mfma_f32_16x16x32_bf16 v[52:55], v[192:195], v[202:205], v[160:163]
	s_nop 1
	v_permlane16_swap_b32_e32 v89, v168
	v_add_f32_e32 v89, v89, v168
	v_mov_b32_e32 v168, v89
	s_nop 1
	v_permlane32_swap_b32_e32 v89, v168
	v_cvt_pk_bf16_f32 v162, v164, v165
	v_cvt_pk_bf16_f32 v163, v166, v167
	global_store_dwordx2 v[92:93], v[162:163], off
	s_and_saveexec_b64 s[0:1], s[58:59]
	s_cbranch_execz .LBB0_362
	v_add_f32_e32 v89, v89, v168
	ds_write_b32 v114, v89

.LBB0_373:
	ds_read_b128 v[160:163], v156 offset:34816
	ds_read_b128 v[164:167], v156 offset:34880
	ds_read_b128 v[168:171], v156 offset:17408
	ds_read_b128 v[172:175], v156 offset:17472
	ds_read_b128 v[176:179], v138
	ds_read_b128 v[180:183], v138 offset:64
	ds_read_b128 v[184:187], v138 offset:4352
	ds_read_b128 v[188:191], v138 offset:4416
	ds_read_b128 v[192:195], v156 offset:34944
	ds_read_b128 v[202:205], v156 offset:35008
	ds_read_b128 v[206:209], v156 offset:17536
	ds_read_b128 v[210:213], v156 offset:17600
	ds_read_b128 v[214:217], v138 offset:128
	ds_read_b128 v[236:239], v138 offset:192
	ds_read_b128 v[240:243], v138 offset:4480
	ds_read_b128 v[244:247], v138 offset:4544
	s_waitcnt lgkmcnt(11)
	v_mfma_f32_16x16x32_bf16 v[248:251], v[160:163], v[176:179], 0
	v_mfma_f32_16x16x32_bf16 v[176:179], v[168:171], v[176:179], 0
	s_waitcnt lgkmcnt(9)
	v_mfma_f32_16x16x32_bf16 v[160:163], v[160:163], v[184:187], 0
	v_mfma_f32_16x16x32_bf16 v[168:171], v[168:171], v[184:187], 0
	v_mfma_f32_16x16x32_bf16 v[184:187], v[164:167], v[180:183], v[248:251]
	v_mfma_f32_16x16x32_bf16 v[176:179], v[172:175], v[180:183], v[176:179]
	s_waitcnt lgkmcnt(8)
	v_mfma_f32_16x16x32_bf16 v[160:163], v[164:167], v[188:191], v[160:163]
	v_mfma_f32_16x16x32_bf16 v[164:167], v[172:175], v[188:191], v[168:171]
	s_waitcnt lgkmcnt(3)
	v_mfma_f32_16x16x32_bf16 v[168:171], v[192:195], v[214:217], v[184:187]
	v_mfma_f32_16x16x32_bf16 v[172:175], v[206:209], v[214:217], v[176:179]
	s_waitcnt lgkmcnt(1)
	v_mfma_f32_16x16x32_bf16 v[160:163], v[192:195], v[240:243], v[160:163]
	s_nop 0
	ds_read_b128 v[176:179], v139
	ds_read_b128 v[180:183], v140 offset:52224
	ds_read_b128 v[184:187], v141 offset:54528
	ds_read_b128 v[188:191], v142 offset:56832
	ds_read_b128 v[192:195], v143 offset:59136
	v_mfma_f32_16x16x32_bf16 v[164:167], v[206:209], v[240:243], v[164:167]
	v_mfma_f32_16x16x32_bf16 v[168:171], v[202:205], v[236:239], v[168:171]
	v_mfma_f32_16x16x32_bf16 v[172:175], v[210:213], v[236:239], v[172:175]
	s_waitcnt lgkmcnt(5)
	v_mfma_f32_16x16x32_bf16 v[160:163], v[202:205], v[244:247], v[160:163]
	v_mfma_f32_16x16x32_bf16 v[164:167], v[210:213], v[244:247], v[164:167]
	ds_read_b32 v88, v120
	ds_read_b128 v[202:205], v131
	s_waitcnt lgkmcnt(0)
	v_pk_add_f32 v[198:199], v[88:89], v[202:203] op_sel:[0,0] op_sel_hi:[0,1] neg_lo:[0,1] neg_hi:[0,1]
	v_pk_add_f32 v[222:223], v[88:89], v[204:205] op_sel:[0,0] op_sel_hi:[0,1] neg_lo:[0,1] neg_hi:[0,1]
	v_pk_mul_f32 v[198:199], v[198:199], s[100:101]
	v_pk_mul_f32 v[222:223], v[222:223], s[100:101]
	v_exp_f32_e32 v198, v198
	v_exp_f32_e32 v199, v199
	v_exp_f32_e32 v222, v222
	v_exp_f32_e32 v223, v223
	v_pk_mul_f32 v[198:199], v[172:173], v[198:199]
	v_pk_mul_f32 v[222:223], v[174:175], v[222:223]
	v_cndmask_b32_e64 v198, v198, 0, s[42:43]
	v_cndmask_b32_e64 v199, 0, v199, s[44:45]
	v_cndmask_b32_e64 v222, v222, 0, s[46:47]
	v_cndmask_b32_e64 v223, v223, 0, s[48:49]
	v_cvt_pk_bf16_f32 v54, v198, v199
	v_cvt_pk_bf16_f32 v55, v222, v223
	ds_write_b64 v144, v[54:55]
	ds_read_b32 v55, v121
	ds_read_b128 v[172:175], v131
	v_mul_f32_e32 v54, 0x3fb8aa3b, v88
	v_exp_f32_e32 v54, v54
	s_waitcnt lgkmcnt(0)
	v_mul_f32_e32 v88, 0x3fb8aa3b, v55
	v_pk_add_f32 v[198:199], v[54:55], v[172:173] op_sel:[1,0] op_sel_hi:[1,1] neg_lo:[0,1] neg_hi:[0,1]
	v_pk_add_f32 v[222:223], v[54:55], v[174:175] op_sel:[1,0] op_sel_hi:[1,1] neg_lo:[0,1] neg_hi:[0,1]
	v_pk_mul_f32 v[198:199], v[198:199], s[100:101]
	v_pk_mul_f32 v[222:223], v[222:223], s[100:101]
	v_exp_f32_e32 v198, v198
	v_exp_f32_e32 v199, v199
	v_exp_f32_e32 v222, v222
	v_exp_f32_e32 v223, v223
	v_exp_f32_e32 v88, v88
	v_pk_mul_f32 v[198:199], v[164:165], v[198:199]
	v_pk_mul_f32 v[222:223], v[166:167], v[222:223]
	v_cndmask_b32_e64 v198, v198, 0, s[50:51]
	v_cndmask_b32_e64 v199, 0, v199, s[52:53]
	v_cndmask_b32_e64 v222, v222, 0, s[54:55]
	v_cndmask_b32_e64 v223, v223, 0, s[56:57]
	v_cvt_pk_bf16_f32 v164, v198, v199
	v_cvt_pk_bf16_f32 v165, v222, v223
	ds_write_b64 v145, v[164:165]
	v_mul_f32_e32 v2, 0x3fb8aa3b, v2
	v_exp_f32_e32 v2, v2
	ds_read_b128 v[164:167], v159
	ds_read_b128 v[172:175], v146 offset:52224
	v_add_u32_e32 v55, v122, v111
	v_pk_mul_f32 v[50:51], v[50:51], v[2:3] op_sel_hi:[1,0]
	v_pk_mul_f32 v[48:49], v[48:49], v[2:3] op_sel_hi:[1,0]
	v_pk_mul_f32 v[42:43], v[42:43], v[2:3] op_sel_hi:[1,0]
	v_pk_mul_f32 v[40:41], v[40:41], v[2:3] op_sel_hi:[1,0]
	v_mfma_f32_16x16x32_bf16 v[48:51], v[180:183], v[176:179], v[48:51]
	v_mul_f32_e64 v46, v46, v2
	v_mul_f32_e64 v47, v47, v2
	v_pk_mul_f32 v[44:45], v[44:45], v[2:3] op_sel_hi:[1,0]
	v_pk_mul_f32 v[38:39], v[38:39], v[2:3] op_sel_hi:[1,0]
	v_pk_mul_f32 v[36:37], v[36:37], v[2:3] op_sel_hi:[1,0]
	v_mfma_f32_16x16x32_bf16 v[40:43], v[184:187], v[176:179], v[40:43]
	v_add_u32_e32 v2, v122, v113
	v_mfma_f32_16x16x32_bf16 v[44:47], v[188:191], v[176:179], v[44:47]
	v_mfma_f32_16x16x32_bf16 v[36:39], v[192:195], v[176:179], v[36:39]
	ds_read_b128 v[176:179], v147 offset:54528
	ds_read_b128 v[180:183], v148 offset:56832
	s_waitcnt lgkmcnt(2)
	v_mfma_f32_16x16x32_bf16 v[48:51], v[172:175], v[164:167], v[48:51]
	ds_read_b128 v[172:175], v149 offset:59136
	s_waitcnt lgkmcnt(0)
	s_barrier
	s_waitcnt lgkmcnt(2)
	v_mfma_f32_16x16x32_bf16 v[40:43], v[176:179], v[164:167], v[40:43]
	ds_read_b128 v[176:179], v2
	ds_read_b128 v[184:187], v55
	s_waitcnt lgkmcnt(3)
	v_mfma_f32_16x16x32_bf16 v[44:47], v[180:183], v[164:167], v[44:47]
	ds_read_b128 v[180:183], v150
	ds_read_b128 v[188:191], v150 offset:64
	ds_read_b128 v[192:195], v150 offset:2304
	ds_read_b128 v[202:205], v150 offset:2368
	s_waitcnt lgkmcnt(6)
	v_mfma_f32_16x16x32_bf16 v[36:39], v[172:175], v[164:167], v[36:39]
	v_mul_f32_e64 v166, v170, v54
	v_mul_f32_e64 v167, v171, v54
	v_pk_mul_f32 v[164:165], v[168:169], v[54:55] op_sel_hi:[1,0]
	v_pk_mul_f32 v[162:163], v[162:163], v[88:89] op_sel_hi:[1,0]
	v_pk_mul_f32 v[160:161], v[160:161], v[88:89] op_sel_hi:[1,0]
	v_cvt_pk_bf16_f32 v54, v48, v49
	v_cvt_pk_bf16_f32 v55, v50, v51
	v_cvt_pk_bf16_f32 v88, v40, v41
	v_cvt_pk_bf16_f32 v89, v42, v43
	ds_write2_b64 v157, v[54:55], v[88:89] offset1:4
	v_cvt_pk_bf16_f32 v54, v44, v45
	v_cvt_pk_bf16_f32 v55, v46, v47
	v_cvt_pk_bf16_f32 v88, v36, v37
	v_cvt_pk_bf16_f32 v89, v38, v39
	ds_write2_b64 v157, v[54:55], v[88:89] offset0:8 offset1:12
	s_waitcnt vmcnt(9)
	v_lshlrev_b32_e32 v54, 16, v52
	v_and_b32_e32 v55, 0xffff0000, v52
	v_mul_f32_e32 v2, 0xbfb8aa3b, v54
	v_exp_f32_e32 v2, v2
	v_mul_f32_e32 v52, 0xbfb8aa3b, v55
	v_exp_f32_e32 v52, v52
	s_waitcnt lgkmcnt(5)
	v_mfma_f32_16x16x32_bf16 v[164:167], v[176:179], v[180:183], v[164:167]
	ds_read_b64 v[88:89], v132
	v_add_f32_e32 v2, 1.0, v2
	v_rcp_f32_e32 v156, v2
	v_add_f32_e32 v2, 1.0, v52
	s_waitcnt lgkmcnt(4)
	v_mfma_f32_16x16x32_bf16 v[158:161], v[176:179], v[192:195], v[160:163]
	v_rcp_f32_e32 v157, v2
	v_lshlrev_b32_e32 v52, 16, v53
	v_and_b32_e32 v53, 0xffff0000, v53
	v_mfma_f32_16x16x32_bf16 v[162:165], v[184:187], v[188:191], v[164:167]
	v_mul_f32_e64 v54, v156, v54
	v_mul_f32_e64 v55, v157, v55
	v_mul_f32_e32 v2, 0xbfb8aa3b, v52
	v_exp_f32_e32 v2, v2
	s_waitcnt lgkmcnt(0)
	v_lshlrev_b32_e32 v166, 16, v88
	v_and_b32_e32 v167, 0xffff0000, v88
	s_nop 0
	v_pk_fma_f32 v[162:163], v[0:1], v[166:167], v[162:163]
	v_add_f32_e32 v2, 1.0, v2
	v_pk_mul_f32 v[156:157], v[54:55], v[162:163]
	v_mul_f32_e32 v54, 0xbfb8aa3b, v53
	v_exp_f32_e32 v88, v54
	v_rcp_f32_e32 v162, v2
	v_pk_mul_f32 v[54:55], v[156:157], v[156:157]
	v_cvt_pk_bf16_f32 v156, v156, v157
	v_add_f32_e32 v2, 1.0, v88
	v_rcp_f32_e32 v163, v2
	v_lshlrev_b32_e32 v88, 16, v89
	v_and_b32_e32 v89, 0xffff0000, v89
	v_pk_fma_f32 v[88:89], v[0:1], v[88:89], v[164:165]
	v_pk_mul_f32 v[52:53], v[162:163], v[52:53]
	v_add_f32_e32 v2, v54, v55
	v_pk_mul_f32 v[162:163], v[52:53], v[88:89]
	v_lshl_add_u64 v[92:93], v[86:87], 0, v[92:93]
	v_pk_mul_f32 v[52:53], v[162:163], v[162:163]
	v_cvt_pk_bf16_f32 v157, v162, v163
	v_add_f32_e32 v2, v52, v2
	v_add_f32_e32 v2, v53, v2
	v_mov_b32_e32 v88, v2
	v_mfma_f32_16x16x32_bf16 v[52:55], v[184:187], v[202:205], v[158:161]
	global_store_dwordx2 v[92:93], v[156:157], off
	s_nop 1
	v_permlane16_swap_b32_e32 v2, v88
	v_add_f32_e32 v2, v2, v88
	v_mov_b32_e32 v88, v2
	s_nop 1
	v_permlane32_swap_b32_e32 v2, v88
	s_and_saveexec_b64 s[0:1], s[58:59]
	s_cbranch_execz .LBB0_375
	v_add_f32_e32 v2, v2, v88
	ds_write_b32 v114, v2
